# P1 full-line stores + sample QK batched reads + P1 first K-iteration peeled with C=0 MFMAs (no accumulator zeroing)
# speedup vs baseline: 1.0139x; 1.0139x over previous
; #define PG8_STAGE(bufoff, gbase, voff) do { _Pragma("unroll") for (int _i = 0; _i < 2; ++_i) \
;         __builtin_amdgcn_global_load_lds((const unsigned*)((const char*)(gbase) + (voff)[_i]), (PG8_LAS unsigned*)(lds + (bufoff) + ldsw + _i * 8192), 16, 0, 0); } while (0)
; #define PG8_LDA(dst, b, h) do { _Pragma("unroll") for (int m = 0; m < 4; ++m) _Pragma("unroll") for (int k = 0; k < 2; ++k) dst[m][k] = *(const PG8_LAS bf16x8*)(lds + PG8_SA(b, h) + aoff + m * 2048 + k * 1024); } while (0)
; #define PG8_LDB(dst, b, h) do { _Pragma("unroll") for (int n = 0; n < 2; ++n) _Pragma("unroll") for (int k = 0; k < 2; ++k) dst[n][k] = *(const PG8_LAS bf16x8*)(lds + PG8_SB(b, h) + boff + n * 2048 + k * 1024); } while (0)
; #define PG8_MMA(ai, bj, At, Bt) do { __builtin_amdgcn_s_setprio(1); _Pragma("unroll") for (int m = 0; m < 4; ++m) _Pragma("unroll") for (int n = 0; n < 2; ++n) _Pragma("unroll") for (int k = 0; k < 2; ++k) \
;         acc[ai][bj][m][n] = __builtin_amdgcn_mfma_f32_16x16x32_bf16(Bt[n][k], At[m][k], acc[ai][bj][m][n], 0, 0, 0); __builtin_amdgcn_s_setprio(0); } while (0)
; #define PG8_WAIT_V(n) asm volatile("s_waitcnt vmcnt(" #n ")" ::: "memory")
; #define PG8_BAR __builtin_amdgcn_s_barrier()
; template <class Epi, class Sched, bool ALIGN_EPI>
; __device__ __forceinline__ unsigned long long gemm_phase(PG8_LAS unsigned char* lds, const Gemm g, const Sched& S, const Epi& E, const int probe_id) {
;     ...
;         const char* nA = has_next ? (const char*)g.A + (size_t)nxt.pm * tstepA + (size_t)nxt.kp * K * 2 : cA; const char* nB = has_next ? (const char*)g.Bt + (size_t)nxt.pn * tstepB + (size_t)nxt.kp * K * 2 : cB;
;         for (int t = 0; t < nt; t += 2) {
;             const bool last = (t == nt - 2);
;             const char* a1 = cA + (size_t)(t + 1) * kstep;
;             const char* a2 = last ? nA : cA + (size_t)(t + 2) * kstep; const char* b2 = last ? nB : cB + (size_t)(t + 2) * kstep;
;             const char* a3 = a2 + kstep; const char* b3 = b2 + kstep;
;             PG8_LDB(B0, 0, 0); PG8_LDB(B1, 0, 1); PG8_SCHED; PG8_LDA(At, 0, 0); PG8_STAGE(PG8_SA(1, 1), a1 + hstepA, voffA);
;             PG8_WAIT_V(8); PG8_WAIT_L(0); PG8_BAR; PG8_MMA(0, 0, At, B0); PG8_MMA(0, 1, At, B1); PG8_BAR; PG8_SCHED;
;             PG8_LDA(At, 0, 1); PG8_STAGE(PG8_SB(0, 0), b2, voffB); PG8_STAGE(PG8_SB(0, 1), b2 + hstepB, voffB); PG8_STAGE(PG8_SA(0, 0), a2, voffA);
.LBB0_126:
	s_mov_b32 s68, s29
	s_ashr_i32 s69, s29, 31
	s_lshl_b64 s[10:11], s[68:69], 19
	s_add_u32 s80, s3, s10
	s_addc_u32 s81, s12, s11
	s_mov_b32 s70, s5
	s_and_b64 s[10:11], s[78:79], exec
	s_cselect_b32 s2, s81, s7
	s_cselect_b32 s5, s80, s6
	s_ashr_i32 s71, s70, 31
	s_lshl_b64 s[10:11], s[70:71], 19
	s_add_u32 s82, s13, s10
	s_addc_u32 s83, s14, s11
	s_and_b64 s[10:11], s[78:79], exec
	s_cselect_b32 s29, s83, s9
	s_cselect_b32 s56, s82, s8
	s_add_u32 s6, s6, 0x40080
	s_addc_u32 s7, s7, 0
	s_add_u32 s69, s8, 0x100
	s_addc_u32 s71, s9, 0
	s_mov_b32 s76, -2
	ds_read_b128 v[130:133], v180
	ds_read_b128 v[134:137], v180 offset:1024
	ds_read_b128 v[138:141], v180 offset:2048
	ds_read_b128 v[142:145], v180 offset:3072
	ds_read_b128 v[164:167], v181
	ds_read_b128 v[168:171], v181 offset:1024
	ds_read_b128 v[172:175], v181 offset:2048
	ds_read_b128 v[188:191], v181 offset:3072
	s_add_u32 s8, s6, 0xfffc0080
	s_addc_u32 s9, s7, -1
	s_cmp_eq_u32 s76, 12
	s_cselect_b32 s11, s2, s9
	s_cselect_b32 s10, s5, s8
	s_cselect_b32 s9, s29, s71
	s_cselect_b32 s8, s56, s69
	v_lshl_add_u64 v[176:177], s[6:7], 0, v[158:159]
	s_add_i32 m0, s34, 0xc000
	ds_read_b128 v[192:195], v182
	ds_read_b128 v[196:199], v182 offset:1024
	ds_read_b128 v[200:203], v182 offset:2048
	ds_read_b128 v[204:207], v182 offset:3072
	ds_read_b128 v[208:211], v182 offset:4096
	ds_read_b128 v[212:215], v182 offset:5120
	ds_read_b128 v[216:219], v182 offset:6144
	ds_read_b128 v[220:223], v182 offset:7168
	global_load_lds_dwordx4 v[176:177], off
	v_lshl_add_u64 v[176:177], s[6:7], 0, v[160:161]
	s_add_i32 m0, s34, 0xe000
	s_nop 0
	global_load_lds_dwordx4 v[176:177], off
	s_waitcnt vmcnt(8)
	s_waitcnt lgkmcnt(0)
	s_barrier
	s_setprio 1
	s_waitcnt lgkmcnt(0)
	v_mfma_f32_16x16x32_bf16 v[126:129], v[130:133], v[192:195], 0
	v_mfma_f32_16x16x32_bf16 v[122:125], v[138:141], v[192:195], 0
	v_mfma_f32_16x16x32_bf16 v[110:113], v[130:133], v[200:203], 0
	v_mfma_f32_16x16x32_bf16 v[106:109], v[138:141], v[200:203], 0
	v_mfma_f32_16x16x32_bf16 v[94:97], v[130:133], v[208:211], 0
	v_mfma_f32_16x16x32_bf16 v[90:93], v[138:141], v[208:211], 0
	v_mfma_f32_16x16x32_bf16 v[78:81], v[130:133], v[216:219], 0
	v_mfma_f32_16x16x32_bf16 v[74:77], v[138:141], v[216:219], 0
	v_mfma_f32_16x16x32_bf16 v[126:129], v[134:137], v[196:199], v[126:129]
	v_mfma_f32_16x16x32_bf16 v[122:125], v[142:145], v[196:199], v[122:125]
	v_mfma_f32_16x16x32_bf16 v[110:113], v[134:137], v[204:207], v[110:113]
	v_mfma_f32_16x16x32_bf16 v[106:109], v[142:145], v[204:207], v[106:109]
	v_mfma_f32_16x16x32_bf16 v[94:97], v[134:137], v[212:215], v[94:97]
	v_mfma_f32_16x16x32_bf16 v[90:93], v[142:145], v[212:215], v[90:93]
	v_mfma_f32_16x16x32_bf16 v[78:81], v[134:137], v[220:223], v[78:81]
	v_mfma_f32_16x16x32_bf16 v[74:77], v[142:145], v[220:223], v[74:77]
	s_setprio 0
	s_setprio 1
	v_mfma_f32_16x16x32_bf16 v[118:121], v[164:167], v[192:195], 0
	v_mfma_f32_16x16x32_bf16 v[114:117], v[172:175], v[192:195], 0
	v_mfma_f32_16x16x32_bf16 v[102:105], v[164:167], v[200:203], 0
	v_mfma_f32_16x16x32_bf16 v[98:101], v[172:175], v[200:203], 0
	v_mfma_f32_16x16x32_bf16 v[86:89], v[164:167], v[208:211], 0
	v_mfma_f32_16x16x32_bf16 v[82:85], v[172:175], v[208:211], 0
	v_mfma_f32_16x16x32_bf16 v[70:73], v[164:167], v[216:219], 0
	v_mfma_f32_16x16x32_bf16 v[66:69], v[172:175], v[216:219], 0
	v_mfma_f32_16x16x32_bf16 v[118:121], v[168:171], v[196:199], v[118:121]
	v_mfma_f32_16x16x32_bf16 v[114:117], v[188:191], v[196:199], v[114:117]
	v_mfma_f32_16x16x32_bf16 v[102:105], v[168:171], v[204:207], v[102:105]
	v_mfma_f32_16x16x32_bf16 v[98:101], v[188:191], v[204:207], v[98:101]
	v_mfma_f32_16x16x32_bf16 v[86:89], v[168:171], v[212:215], v[86:89]
	v_mfma_f32_16x16x32_bf16 v[82:85], v[188:191], v[212:215], v[82:85]
	v_mfma_f32_16x16x32_bf16 v[70:73], v[168:171], v[220:223], v[70:73]
	v_mfma_f32_16x16x32_bf16 v[66:69], v[188:191], v[220:223], v[66:69]
	s_setprio 0
	s_barrier
	s_add_i32 s86, s57, s15
	v_lshl_add_u64 v[176:177], s[8:9], 0, v[150:151]
	s_mov_b32 m0, s86
	ds_read_b128 v[192:195], v182 offset:16384
	ds_read_b128 v[196:199], v182 offset:17408
	ds_read_b128 v[200:203], v182 offset:18432
	ds_read_b128 v[204:207], v182 offset:19456
	ds_read_b128 v[208:211], v182 offset:20480
	ds_read_b128 v[212:215], v182 offset:21504
	ds_read_b128 v[216:219], v182 offset:22528
	ds_read_b128 v[220:223], v182 offset:23552
	global_load_lds_dwordx4 v[176:177], off
	s_add_i32 m0, s86, 0x2000
	s_add_u32 s86, s8, 0x40000
	v_lshl_add_u64 v[224:225], s[8:9], 0, v[154:155]
	s_addc_u32 s87, s9, 0
	s_add_i32 s88, s60, s15
	global_load_lds_dwordx4 v[224:225], off
	v_lshl_add_u64 v[226:227], s[86:87], 0, v[150:151]
	s_mov_b32 m0, s88
	v_lshl_add_u64 v[228:229], s[10:11], 0, v[152:153]
	global_load_lds_dwordx4 v[226:227], off
	v_lshl_add_u64 v[226:227], s[86:87], 0, v[154:155]
	s_add_i32 m0, s88, 0x2000
	s_nop 0
	global_load_lds_dwordx4 v[226:227], off
	v_lshl_add_u64 v[226:227], s[10:11], 0, v[148:149]
	s_mov_b32 m0, s34
	s_nop 0
	global_load_lds_dwordx4 v[226:227], off
	s_mov_b32 m0, s35
	s_nop 0
	global_load_lds_dwordx4 v[228:229], off
	s_waitcnt vmcnt(8)
	s_waitcnt lgkmcnt(0)
	s_barrier
; #define PG8_STAGE(bufoff, gbase, voff) do { _Pragma("unroll") for (int _i = 0; _i < 2; ++_i) \
;         __builtin_amdgcn_global_load_lds((const unsigned*)((const char*)(gbase) + (voff)[_i]), (PG8_LAS unsigned*)(lds + (bufoff) + ldsw + _i * 8192), 16, 0, 0); } while (0)
; #define PG8_LDA(dst, b, h) do { _Pragma("unroll") for (int m = 0; m < 4; ++m) _Pragma("unroll") for (int k = 0; k < 2; ++k) dst[m][k] = *(const PG8_LAS bf16x8*)(lds + PG8_SA(b, h) + aoff + m * 2048 + k * 1024); } while (0)
; #define PG8_LDB(dst, b, h) do { _Pragma("unroll") for (int n = 0; n < 2; ++n) _Pragma("unroll") for (int k = 0; k < 2; ++k) dst[n][k] = *(const PG8_LAS bf16x8*)(lds + PG8_SB(b, h) + boff + n * 2048 + k * 1024); } while (0)
; #define PG8_MMA(ai, bj, At, Bt) do { __builtin_amdgcn_s_setprio(1); _Pragma("unroll") for (int m = 0; m < 4; ++m) _Pragma("unroll") for (int n = 0; n < 2; ++n) _Pragma("unroll") for (int k = 0; k < 2; ++k) \
;         acc[ai][bj][m][n] = __builtin_amdgcn_mfma_f32_16x16x32_bf16(Bt[n][k], At[m][k], acc[ai][bj][m][n], 0, 0, 0); __builtin_amdgcn_s_setprio(0); } while (0)
; #define PG8_WAIT_V(n) asm volatile("s_waitcnt vmcnt(" #n ")" ::: "memory")
; #define PG8_WAIT_L(n) asm volatile("s_waitcnt lgkmcnt(" #n ")" ::: "memory")
; #define PG8_BAR __builtin_amdgcn_s_barrier()
; #define PG8_SCHED __builtin_amdgcn_sched_barrier(0)
; template <class Epi, class Sched, bool ALIGN_EPI>
; __device__ __forceinline__ unsigned long long gemm_phase(PG8_LAS unsigned char* lds, const Gemm g, const Sched& S, const Epi& E, const int probe_id) {
;     ...
;             PG8_LDA(At, 0, 1); PG8_STAGE(PG8_SB(0, 0), b2, voffB); PG8_STAGE(PG8_SB(0, 1), b2 + hstepB, voffB); PG8_STAGE(PG8_SA(0, 0), a2, voffA);
;             PG8_WAIT_V(8); PG8_WAIT_L(0); PG8_BAR; PG8_MMA(1, 0, At, B0); PG8_MMA(1, 1, At, B1); PG8_BAR; PG8_SCHED;
;             PG8_LDB(B0, 1, 0); PG8_LDB(B1, 1, 1); PG8_SCHED; PG8_LDA(At, 1, 0); PG8_STAGE(PG8_SA(0, 1), a2 + hstepA, voffA);
;             PG8_WAIT_V(8); PG8_WAIT_L(0); PG8_BAR; PG8_MMA(0, 0, At, B0); PG8_MMA(0, 1, At, B1); PG8_BAR; PG8_SCHED;
	s_setprio 1
	s_waitcnt lgkmcnt(0)
	v_mfma_f32_16x16x32_bf16 v[62:65], v[130:133], v[192:195], 0
	v_mfma_f32_16x16x32_bf16 v[58:61], v[138:141], v[192:195], 0
	v_mfma_f32_16x16x32_bf16 v[46:49], v[130:133], v[200:203], 0
	v_mfma_f32_16x16x32_bf16 v[42:45], v[138:141], v[200:203], 0
	v_mfma_f32_16x16x32_bf16 v[30:33], v[130:133], v[208:211], 0
	v_mfma_f32_16x16x32_bf16 v[26:29], v[138:141], v[208:211], 0
	v_mfma_f32_16x16x32_bf16 v[14:17], v[130:133], v[216:219], 0
	v_mfma_f32_16x16x32_bf16 v[10:13], v[138:141], v[216:219], 0
	v_mfma_f32_16x16x32_bf16 v[62:65], v[134:137], v[196:199], v[62:65]
	v_mfma_f32_16x16x32_bf16 v[58:61], v[142:145], v[196:199], v[58:61]
	v_mfma_f32_16x16x32_bf16 v[46:49], v[134:137], v[204:207], v[46:49]
	v_mfma_f32_16x16x32_bf16 v[42:45], v[142:145], v[204:207], v[42:45]
	v_mfma_f32_16x16x32_bf16 v[30:33], v[134:137], v[212:215], v[30:33]
	v_mfma_f32_16x16x32_bf16 v[26:29], v[142:145], v[212:215], v[26:29]
	v_mfma_f32_16x16x32_bf16 v[14:17], v[134:137], v[220:223], v[14:17]
	v_mfma_f32_16x16x32_bf16 v[10:13], v[142:145], v[220:223], v[10:13]
	s_setprio 0
	s_setprio 1
	v_mfma_f32_16x16x32_bf16 v[54:57], v[164:167], v[192:195], 0
	v_mfma_f32_16x16x32_bf16 v[50:53], v[172:175], v[192:195], 0
	v_mfma_f32_16x16x32_bf16 v[38:41], v[164:167], v[200:203], 0
	v_mfma_f32_16x16x32_bf16 v[34:37], v[172:175], v[200:203], 0
	v_mfma_f32_16x16x32_bf16 v[22:25], v[164:167], v[208:211], 0
	v_mfma_f32_16x16x32_bf16 v[18:21], v[172:175], v[208:211], 0
	v_mfma_f32_16x16x32_bf16 v[6:9], v[164:167], v[216:219], 0
	v_mfma_f32_16x16x32_bf16 v[2:5], v[172:175], v[216:219], 0
	v_mfma_f32_16x16x32_bf16 v[54:57], v[168:171], v[196:199], v[54:57]
	v_mfma_f32_16x16x32_bf16 v[50:53], v[188:191], v[196:199], v[50:53]
	v_mfma_f32_16x16x32_bf16 v[38:41], v[168:171], v[204:207], v[38:41]
	v_mfma_f32_16x16x32_bf16 v[34:37], v[188:191], v[204:207], v[34:37]
	v_mfma_f32_16x16x32_bf16 v[22:25], v[168:171], v[212:215], v[22:25]
	v_mfma_f32_16x16x32_bf16 v[18:21], v[188:191], v[212:215], v[18:21]
	v_mfma_f32_16x16x32_bf16 v[6:9], v[168:171], v[220:223], v[6:9]
	v_mfma_f32_16x16x32_bf16 v[2:5], v[188:191], v[220:223], v[2:5]
	s_setprio 0
	s_barrier
	s_add_i32 s86, 0, 0x18000
	s_add_i32 s87, 0, 0x1c000
	v_add_u32_e32 v142, s86, v147
	v_add_u32_e32 v156, s87, v147
	ds_read_b128 v[130:133], v142
	ds_read_b128 v[134:137], v142 offset:1024
	ds_read_b128 v[138:141], v142 offset:2048
	ds_read_b128 v[142:145], v142 offset:3072
	ds_read_b128 v[164:167], v156
	ds_read_b128 v[168:171], v156 offset:1024
	ds_read_b128 v[172:175], v156 offset:2048
	ds_read_b128 v[188:191], v156 offset:3072
	s_add_u32 s10, s10, 0x40000
	s_addc_u32 s11, s11, 0
	s_mov_b32 m0, s77
	v_lshl_add_u64 v[230:231], s[10:11], 0, v[148:149]
	ds_read_b128 v[192:195], v182 offset:32768
	ds_read_b128 v[196:199], v182 offset:33792
	ds_read_b128 v[200:203], v182 offset:34816
	ds_read_b128 v[204:207], v182 offset:35840
	ds_read_b128 v[208:211], v182 offset:36864
	ds_read_b128 v[212:215], v182 offset:37888
	ds_read_b128 v[216:219], v182 offset:38912
	ds_read_b128 v[220:223], v182 offset:39936
	global_load_lds_dwordx4 v[230:231], off
	v_lshl_add_u64 v[230:231], s[10:11], 0, v[152:153]
	s_mov_b32 m0, s85
	s_nop 0
	global_load_lds_dwordx4 v[230:231], off
	s_waitcnt vmcnt(8)
	s_waitcnt lgkmcnt(0)
	s_barrier
	s_setprio 1
	s_waitcnt lgkmcnt(0)
	v_mfma_f32_16x16x32_bf16 v[126:129], v[130:133], v[192:195], v[126:129]
	v_mfma_f32_16x16x32_bf16 v[122:125], v[138:141], v[192:195], v[122:125]
	v_mfma_f32_16x16x32_bf16 v[110:113], v[130:133], v[200:203], v[110:113]
	v_mfma_f32_16x16x32_bf16 v[106:109], v[138:141], v[200:203], v[106:109]
	v_mfma_f32_16x16x32_bf16 v[94:97], v[130:133], v[208:211], v[94:97]
	v_mfma_f32_16x16x32_bf16 v[90:93], v[138:141], v[208:211], v[90:93]
	v_mfma_f32_16x16x32_bf16 v[78:81], v[130:133], v[216:219], v[78:81]
	v_mfma_f32_16x16x32_bf16 v[74:77], v[138:141], v[216:219], v[74:77]
	v_mfma_f32_16x16x32_bf16 v[126:129], v[134:137], v[196:199], v[126:129]
	v_mfma_f32_16x16x32_bf16 v[122:125], v[142:145], v[196:199], v[122:125]
	v_mfma_f32_16x16x32_bf16 v[110:113], v[134:137], v[204:207], v[110:113]
	v_mfma_f32_16x16x32_bf16 v[106:109], v[142:145], v[204:207], v[106:109]
	v_mfma_f32_16x16x32_bf16 v[94:97], v[134:137], v[212:215], v[94:97]
	v_mfma_f32_16x16x32_bf16 v[90:93], v[142:145], v[212:215], v[90:93]
	v_mfma_f32_16x16x32_bf16 v[78:81], v[134:137], v[220:223], v[78:81]
	v_mfma_f32_16x16x32_bf16 v[74:77], v[142:145], v[220:223], v[74:77]
	s_setprio 0
	s_setprio 1
	v_mfma_f32_16x16x32_bf16 v[118:121], v[164:167], v[192:195], v[118:121]
	v_mfma_f32_16x16x32_bf16 v[114:117], v[172:175], v[192:195], v[114:117]
	v_mfma_f32_16x16x32_bf16 v[102:105], v[164:167], v[200:203], v[102:105]
	v_mfma_f32_16x16x32_bf16 v[98:101], v[172:175], v[200:203], v[98:101]
	v_mfma_f32_16x16x32_bf16 v[86:89], v[164:167], v[208:211], v[86:89]
	v_mfma_f32_16x16x32_bf16 v[82:85], v[172:175], v[208:211], v[82:85]
	v_mfma_f32_16x16x32_bf16 v[70:73], v[164:167], v[216:219], v[70:73]
	v_mfma_f32_16x16x32_bf16 v[66:69], v[172:175], v[216:219], v[66:69]
	v_mfma_f32_16x16x32_bf16 v[118:121], v[168:171], v[196:199], v[118:121]
	v_mfma_f32_16x16x32_bf16 v[114:117], v[188:191], v[196:199], v[114:117]
	v_mfma_f32_16x16x32_bf16 v[102:105], v[168:171], v[204:207], v[102:105]
	v_mfma_f32_16x16x32_bf16 v[98:101], v[188:191], v[204:207], v[98:101]
	v_mfma_f32_16x16x32_bf16 v[86:89], v[168:171], v[212:215], v[86:89]
	v_mfma_f32_16x16x32_bf16 v[82:85], v[188:191], v[212:215], v[82:85]
	v_mfma_f32_16x16x32_bf16 v[70:73], v[168:171], v[220:223], v[70:73]
	v_mfma_f32_16x16x32_bf16 v[66:69], v[188:191], v[220:223], v[66:69]
	s_setprio 0
	s_barrier
; #define PG8_STAGE(bufoff, gbase, voff) do { _Pragma("unroll") for (int _i = 0; _i < 2; ++_i) \
;         __builtin_amdgcn_global_load_lds((const unsigned*)((const char*)(gbase) + (voff)[_i]), (PG8_LAS unsigned*)(lds + (bufoff) + ldsw + _i * 8192), 16, 0, 0); } while (0)
; #define PG8_LDA(dst, b, h) do { _Pragma("unroll") for (int m = 0; m < 4; ++m) _Pragma("unroll") for (int k = 0; k < 2; ++k) dst[m][k] = *(const PG8_LAS bf16x8*)(lds + PG8_SA(b, h) + aoff + m * 2048 + k * 1024); } while (0)
; #define PG8_MMA(ai, bj, At, Bt) do { __builtin_amdgcn_s_setprio(1); _Pragma("unroll") for (int m = 0; m < 4; ++m) _Pragma("unroll") for (int n = 0; n < 2; ++n) _Pragma("unroll") for (int k = 0; k < 2; ++k) \
;         acc[ai][bj][m][n] = __builtin_amdgcn_mfma_f32_16x16x32_bf16(Bt[n][k], At[m][k], acc[ai][bj][m][n], 0, 0, 0); __builtin_amdgcn_s_setprio(0); } while (0)
; #define PG8_WAIT_V(n) asm volatile("s_waitcnt vmcnt(" #n ")" ::: "memory")
; #define PG8_WAIT_L(n) asm volatile("s_waitcnt lgkmcnt(" #n ")" ::: "memory")
; #define PG8_BAR __builtin_amdgcn_s_barrier()
; #define PG8_SCHED __builtin_amdgcn_sched_barrier(0)
; template <class Epi, class Sched, bool ALIGN_EPI>
; __device__ __forceinline__ unsigned long long gemm_phase(PG8_LAS unsigned char* lds, const Gemm g, const Sched& S, const Epi& E, const int probe_id) {
;     ...
;             PG8_LDA(At, 1, 1); PG8_STAGE(PG8_SB(1, 0), b3, voffB); PG8_STAGE(PG8_SB(1, 1), b3 + hstepB, voffB); PG8_STAGE(PG8_SA(1, 0), a3, voffA);
;             PG8_WAIT_V(8); PG8_WAIT_L(0); PG8_BAR; PG8_MMA(1, 0, At, B0); PG8_MMA(1, 1, At, B1); PG8_BAR; PG8_SCHED;
	s_add_i32 s10, s86, s15
	v_lshl_add_u64 v[176:177], v[176:177], 0, s[30:31]
	s_mov_b32 m0, s10
	ds_read_b128 v[192:195], v182 offset:49152
	ds_read_b128 v[196:199], v182 offset:50176
	ds_read_b128 v[200:203], v182 offset:51200
	ds_read_b128 v[204:207], v182 offset:52224
	ds_read_b128 v[208:211], v182 offset:53248
	ds_read_b128 v[212:215], v182 offset:54272
	ds_read_b128 v[216:219], v182 offset:55296
	ds_read_b128 v[220:223], v182 offset:56320
	global_load_lds_dwordx4 v[176:177], off
	s_add_i32 m0, s10, 0x2000
	s_add_u32 s8, s8, 0x40080
	v_lshl_add_u64 v[176:177], v[224:225], 0, s[30:31]
	s_addc_u32 s9, s9, 0
	s_add_i32 s10, s87, s15
	global_load_lds_dwordx4 v[176:177], off
	v_lshl_add_u64 v[176:177], s[8:9], 0, v[150:151]
	s_mov_b32 m0, s10
	s_nop 0
	global_load_lds_dwordx4 v[176:177], off
	v_lshl_add_u64 v[176:177], s[8:9], 0, v[154:155]
	s_add_i32 m0, s10, 0x2000
	s_nop 0
	global_load_lds_dwordx4 v[176:177], off
	v_lshl_add_u64 v[176:177], v[226:227], 0, s[30:31]
	s_mov_b32 m0, s95
	s_nop 0
	global_load_lds_dwordx4 v[176:177], off
	v_lshl_add_u64 v[176:177], v[228:229], 0, s[30:31]
	s_mov_b32 m0, s97
	s_nop 0
	global_load_lds_dwordx4 v[176:177], off
	s_waitcnt vmcnt(8)
	s_waitcnt lgkmcnt(0)
	s_barrier
	s_setprio 1
	s_waitcnt lgkmcnt(0)
	v_mfma_f32_16x16x32_bf16 v[62:65], v[130:133], v[192:195], v[62:65]
	v_mfma_f32_16x16x32_bf16 v[58:61], v[138:141], v[192:195], v[58:61]
	v_mfma_f32_16x16x32_bf16 v[46:49], v[130:133], v[200:203], v[46:49]
	v_mfma_f32_16x16x32_bf16 v[42:45], v[138:141], v[200:203], v[42:45]
	v_mfma_f32_16x16x32_bf16 v[30:33], v[130:133], v[208:211], v[30:33]
	v_mfma_f32_16x16x32_bf16 v[26:29], v[138:141], v[208:211], v[26:29]
	v_mfma_f32_16x16x32_bf16 v[14:17], v[130:133], v[216:219], v[14:17]
	v_mfma_f32_16x16x32_bf16 v[10:13], v[138:141], v[216:219], v[10:13]
	v_mfma_f32_16x16x32_bf16 v[62:65], v[134:137], v[196:199], v[62:65]
	v_mfma_f32_16x16x32_bf16 v[58:61], v[142:145], v[196:199], v[58:61]
	v_mfma_f32_16x16x32_bf16 v[46:49], v[134:137], v[204:207], v[46:49]
	v_mfma_f32_16x16x32_bf16 v[42:45], v[142:145], v[204:207], v[42:45]
	v_mfma_f32_16x16x32_bf16 v[30:33], v[134:137], v[212:215], v[30:33]
	v_mfma_f32_16x16x32_bf16 v[26:29], v[142:145], v[212:215], v[26:29]
	v_mfma_f32_16x16x32_bf16 v[14:17], v[134:137], v[220:223], v[14:17]
	v_mfma_f32_16x16x32_bf16 v[10:13], v[142:145], v[220:223], v[10:13]
	s_setprio 0
	s_setprio 1
	v_mfma_f32_16x16x32_bf16 v[54:57], v[164:167], v[192:195], v[54:57]
	v_mfma_f32_16x16x32_bf16 v[50:53], v[172:175], v[192:195], v[50:53]
	v_mfma_f32_16x16x32_bf16 v[38:41], v[164:167], v[200:203], v[38:41]
	v_mfma_f32_16x16x32_bf16 v[34:37], v[172:175], v[200:203], v[34:37]
	v_mfma_f32_16x16x32_bf16 v[22:25], v[164:167], v[208:211], v[22:25]
	v_mfma_f32_16x16x32_bf16 v[18:21], v[172:175], v[208:211], v[18:21]
	v_mfma_f32_16x16x32_bf16 v[6:9], v[164:167], v[216:219], v[6:9]
	v_mfma_f32_16x16x32_bf16 v[2:5], v[172:175], v[216:219], v[2:5]
	v_mfma_f32_16x16x32_bf16 v[54:57], v[168:171], v[196:199], v[54:57]
	v_mfma_f32_16x16x32_bf16 v[50:53], v[188:191], v[196:199], v[50:53]
	v_mfma_f32_16x16x32_bf16 v[38:41], v[168:171], v[204:207], v[38:41]
	v_mfma_f32_16x16x32_bf16 v[34:37], v[188:191], v[204:207], v[34:37]
	v_mfma_f32_16x16x32_bf16 v[22:25], v[168:171], v[212:215], v[22:25]
	v_mfma_f32_16x16x32_bf16 v[18:21], v[188:191], v[212:215], v[18:21]
	v_mfma_f32_16x16x32_bf16 v[6:9], v[168:171], v[220:223], v[6:9]
	v_mfma_f32_16x16x32_bf16 v[2:5], v[188:191], v[220:223], v[2:5]
	s_setprio 0
	s_barrier
	s_add_i32 s76, s76, 2
	s_add_u32 s6, s6, 0x100
	s_addc_u32 s7, s7, 0
	s_add_u32 s69, s69, 0x100
	s_addc_u32 s71, s71, 0
